# gate phase rewritten by hand as a rolled loop (lsb in LDS, grouped q/k loads ahead of stores), same fp32 math; plus earlier wait fixes
# speedup vs baseline: 1.0119x; 1.0119x over previous
; #define LAS __attribute__((address_space(3)))
; DI float logsig16(float z) { return (fminf(z, 0.f) - __logf(1.0f + __expf(-fabsf(z)))) * (1.0f / 16.0f); }
; DI void gla_gate_phase(const Params& P, LAS unsigned char* lds, int lj) {
;     ...
;   float wf[16], wb[16];
; #pragma unroll
;   for (int j = 0; j < 16; ++j) { wf[j] = Wf[j * 512 + col]; wb[j] = Wb[j * 512 + col]; }
;   const float bf_ = P.in[9][(size_t)lj * 512 + col], bb_ = P.in[11][(size_t)lj * 512 + col];
;   LAS float* zL = (LAS float*)lds;
;   for (int item = blockIdx.x; item < 512; item += gridDim.x) {
;     __syncthreads();
;     { const int row = tid >> 3, part = tid & 7; *(LAS f32x4*)(zL + row * 32 + part * 4) = *(const f32x4*)(zbuf + ((size_t)item * 64 + row) * 32 + part * 4); }
;     __syncthreads();
;     float lsb[64]; float totb = 0.f;
; #pragma unroll
;     for (int i = 0; i < 64; ++i) {
;       float z = bb_;
; #pragma unroll
;       for (int j4 = 0; j4 < 4; ++j4) { const f32x4 zz = *(const LAS f32x4*)(zL + i * 32 + 16 + j4 * 4); z += zz[0] * wb[j4 * 4] + zz[1] * wb[j4 * 4 + 1] + zz[2] * wb[j4 * 4 + 2] + zz[3] * wb[j4 * 4 + 3]; }
;       lsb[i] = logsig16(z); totb += lsb[i];
;     }
.LBB0_178:
	v_readlane_b32 s0, v253, 46
	v_readlane_b32 s1, v253, 47
	v_readlane_b32 s20, v253, 52
	v_mov_b32_e32 v2, v220
	s_andn2_b64 vcc, exec, s[0:1]
	v_readlane_b32 s21, v253, 53
	s_movk_i32 s29, 0x4000
	s_movk_i32 s34, 0x6000
	s_mov_b32 s61, 0x800000
	s_mov_b32 s16, 0xbfb8aa3b
	s_movk_i32 s52, 0x1000
	s_movk_i32 s53, 0x3000
	s_movk_i32 s54, 0x7000
	s_mov_b32 s55, 0x3f317217
	s_mov_b32 s56, 0x7f800000
	s_mov_b32 s57, 0x3d800000
	s_mov_b32 s89, 0x2e000
	s_mov_b32 s17, 0x3a000
	s_mov_b32 s28, 0x3c000
	s_mov_b64 s[90:91], 0x48000
	s_mov_b64 s[92:93], 0x3000
	s_mov_b64 s[82:83], 0x4800
	s_mov_b64 s[84:85], 0x6000
	s_mov_b64 s[86:87], 0x7800
	s_mov_b64 s[62:63], 0x9000
	s_mov_b64 s[72:73], 0xa800
	s_mov_b64 s[96:97], 0xc000
	s_mov_b64 s[74:75], 0xd800
	s_mov_b64 s[66:67], 0xf000
	s_mov_b64 s[76:77], 0x5800
	s_mov_b32 s70, 0x34000
	s_cbranch_vccnz .LBB0_181
	v_readlane_b32 s18, v255, 12
	v_readlane_b32 s36, v254, 39
	v_readlane_b32 s37, v254, 40
	v_readlane_b32 s40, v254, 43
	v_readlane_b32 s41, v254, 44
	v_readlane_b32 s38, v254, 41
	v_readlane_b32 s39, v254, 42
	v_readlane_b32 s46, v254, 45
	v_readlane_b32 s47, v254, 46
	s_mov_b32 s16, 0xbfb8aa3b
	s_mov_b32 s55, 0x3f317217
	s_lshl_b32 s19, s18, 15
	s_add_u32 s36, s36, s19
	s_addc_u32 s37, s37, 0
	s_add_u32 s40, s40, s19
	s_addc_u32 s41, s41, 0
	s_lshl_b32 s19, s18, 11
	s_add_u32 s38, s38, s19
	s_addc_u32 s39, s39, 0
	s_add_u32 s46, s46, s19
	s_addc_u32 s47, s47, 0
	v_lshlrev_b32_e32 v36, 2, v220
	v_lshlrev_b32_e32 v37, 1, v220
	v_lshlrev_b32_e32 v48, 4, v220
	global_load_dword v2, v36, s[36:37]
	global_load_dword v18, v36, s[40:41]
	s_add_u32 s36, s36, 0x800
	s_addc_u32 s37, s37, 0
	s_add_u32 s40, s40, 0x800
	s_addc_u32 s41, s41, 0
	global_load_dword v3, v36, s[36:37]
	global_load_dword v19, v36, s[40:41]
	s_add_u32 s36, s36, 0x800
	s_addc_u32 s37, s37, 0
	s_add_u32 s40, s40, 0x800
	s_addc_u32 s41, s41, 0
	global_load_dword v4, v36, s[36:37]
	global_load_dword v20, v36, s[40:41]
	s_add_u32 s36, s36, 0x800
	s_addc_u32 s37, s37, 0
	s_add_u32 s40, s40, 0x800
	s_addc_u32 s41, s41, 0
	global_load_dword v5, v36, s[36:37]
	global_load_dword v21, v36, s[40:41]
	s_add_u32 s36, s36, 0x800
	s_addc_u32 s37, s37, 0
	s_add_u32 s40, s40, 0x800
	s_addc_u32 s41, s41, 0
	global_load_dword v6, v36, s[36:37]
	global_load_dword v22, v36, s[40:41]
	s_add_u32 s36, s36, 0x800
	s_addc_u32 s37, s37, 0
	s_add_u32 s40, s40, 0x800
	s_addc_u32 s41, s41, 0
	global_load_dword v7, v36, s[36:37]
	global_load_dword v23, v36, s[40:41]
	s_add_u32 s36, s36, 0x800
	s_addc_u32 s37, s37, 0
	s_add_u32 s40, s40, 0x800
	s_addc_u32 s41, s41, 0
	global_load_dword v8, v36, s[36:37]
	global_load_dword v24, v36, s[40:41]
	s_add_u32 s36, s36, 0x800
	s_addc_u32 s37, s37, 0
	s_add_u32 s40, s40, 0x800
	s_addc_u32 s41, s41, 0
	global_load_dword v9, v36, s[36:37]
	global_load_dword v25, v36, s[40:41]
	s_add_u32 s36, s36, 0x800
	s_addc_u32 s37, s37, 0
	s_add_u32 s40, s40, 0x800
	s_addc_u32 s41, s41, 0
	global_load_dword v10, v36, s[36:37]
	global_load_dword v26, v36, s[40:41]
	s_add_u32 s36, s36, 0x800
	s_addc_u32 s37, s37, 0
	s_add_u32 s40, s40, 0x800
	s_addc_u32 s41, s41, 0
	global_load_dword v11, v36, s[36:37]
	global_load_dword v27, v36, s[40:41]
	s_add_u32 s36, s36, 0x800
	s_addc_u32 s37, s37, 0
	s_add_u32 s40, s40, 0x800
	s_addc_u32 s41, s41, 0
	global_load_dword v12, v36, s[36:37]
	global_load_dword v28, v36, s[40:41]
	s_add_u32 s36, s36, 0x800
	s_addc_u32 s37, s37, 0
	s_add_u32 s40, s40, 0x800
	s_addc_u32 s41, s41, 0
	global_load_dword v13, v36, s[36:37]
	global_load_dword v29, v36, s[40:41]
	s_add_u32 s36, s36, 0x800
	s_addc_u32 s37, s37, 0
	s_add_u32 s40, s40, 0x800
	s_addc_u32 s41, s41, 0
	global_load_dword v14, v36, s[36:37]
	global_load_dword v30, v36, s[40:41]
	s_add_u32 s36, s36, 0x800
	s_addc_u32 s37, s37, 0
	s_add_u32 s40, s40, 0x800
	s_addc_u32 s41, s41, 0
	global_load_dword v15, v36, s[36:37]
	global_load_dword v31, v36, s[40:41]
	s_add_u32 s36, s36, 0x800
	s_addc_u32 s37, s37, 0
	s_add_u32 s40, s40, 0x800
	s_addc_u32 s41, s41, 0
	global_load_dword v16, v36, s[36:37]
	global_load_dword v32, v36, s[40:41]
	s_add_u32 s36, s36, 0x800
	s_addc_u32 s37, s37, 0
	s_add_u32 s40, s40, 0x800
	s_addc_u32 s41, s41, 0
	global_load_dword v17, v36, s[36:37]
	global_load_dword v33, v36, s[40:41]
	global_load_dword v34, v36, s[38:39]
	global_load_dword v35, v36, s[46:47]
	v_mov_b32_e32 v38, v37
	v_add_u32_e32 v39, 6144, v37
	v_add_u32_e32 v40, 12288, v37
	v_add_u32_e32 v41, 18432, v37
	v_add_u32_e32 v42, 24576, v37
	v_add_u32_e32 v43, 30720, v37
	v_add_u32_e32 v44, 36864, v37
	v_add_u32_e32 v45, 43008, v37
	v_add_u32_e32 v46, 0x1000, v37
	s_mov_b32 s42, s60
.Lgt_item:
	s_waitcnt vmcnt(0) lgkmcnt(0)
	s_barrier
	s_lshl_b32 s0, s42, 13
	s_add_u32 s44, s6, s0
	s_addc_u32 s45, s7, 0
	s_add_u32 s44, s44, 0x900000
	s_addc_u32 s45, s45, 0
	global_load_dwordx4 v[124:127], v48, s[44:45]
	s_mul_i32 s0, s42, 0x60000
	s_add_u32 s46, s6, s0
	s_addc_u32 s47, s7, 0
	s_add_u32 s46, s46, 0x9a00000
	s_addc_u32 s47, s47, 0
	s_lshl_b32 s0, s42, 16
	s_add_u32 s48, s6, s0
	s_addc_u32 s49, s7, 0
	s_add_u32 s48, s48, 0x5a00000
	s_addc_u32 s49, s49, 0
	s_add_u32 s50, s48, 0x2000000
	s_addc_u32 s51, s49, 0
	global_load_ushort v52, v38, s[46:47]
	global_load_ushort v60, v38, s[46:47] offset:1024
	global_load_ushort v53, v39, s[46:47]
	global_load_ushort v61, v39, s[46:47] offset:1024
	global_load_ushort v54, v40, s[46:47]
	global_load_ushort v62, v40, s[46:47] offset:1024
	global_load_ushort v55, v41, s[46:47]
	global_load_ushort v63, v41, s[46:47] offset:1024
	global_load_ushort v56, v42, s[46:47]
	global_load_ushort v64, v42, s[46:47] offset:1024
	global_load_ushort v57, v43, s[46:47]
	global_load_ushort v65, v43, s[46:47] offset:1024
	global_load_ushort v58, v44, s[46:47]
	global_load_ushort v66, v44, s[46:47] offset:1024
	global_load_ushort v59, v45, s[46:47]
	global_load_ushort v67, v45, s[46:47] offset:1024
	s_waitcnt vmcnt(16)
	ds_write_b128 v48, v[124:127]
	s_waitcnt lgkmcnt(0)
	s_barrier
	v_mov_b32_e32 v130, 0
	v_mov_b32_e32 v49, 0
	v_add_u32_e32 v50, 0x2000, v36
	ds_read_b128 v[84:87], v49 offset:64
	ds_read_b128 v[88:91], v49 offset:80
	ds_read_b128 v[92:95], v49 offset:96
	ds_read_b128 v[96:99], v49 offset:112
	s_mov_b32 s43, 0
; #define LAS __attribute__((address_space(3)))
; DI float logsig16(float z) { return (fminf(z, 0.f) - __logf(1.0f + __expf(-fabsf(z)))) * (1.0f / 16.0f); }
; DI void gla_gate_phase(const Params& P, LAS unsigned char* lds, int lj) {
;     ...
;     float lsb[64]; float totb = 0.f;
; #pragma unroll
;     for (int i = 0; i < 64; ++i) {
;       float z = bb_;
; #pragma unroll
;       for (int j4 = 0; j4 < 4; ++j4) { const f32x4 zz = *(const LAS f32x4*)(zL + i * 32 + 16 + j4 * 4); z += zz[0] * wb[j4 * 4] + zz[1] * wb[j4 * 4 + 1] + zz[2] * wb[j4 * 4 + 2] + zz[3] * wb[j4 * 4 + 3]; }
;       lsb[i] = logsig16(z); totb += lsb[i];
;     }
.Lgt_pre:
	ds_read_b128 v[100:103], v49 offset:192
	ds_read_b128 v[104:107], v49 offset:208
	ds_read_b128 v[108:111], v49 offset:224
	ds_read_b128 v[112:115], v49 offset:240
	s_waitcnt lgkmcnt(4)
	v_mul_f32_e32 v116, v19, v85
	v_fmac_f32_e32 v116, v18, v84
	v_fmac_f32_e32 v116, v20, v86
	v_fmac_f32_e32 v116, v21, v87
	v_add_f32_e32 v121, v35, v116
	v_mul_f32_e32 v116, v23, v89
	v_fmac_f32_e32 v116, v22, v88
	v_fmac_f32_e32 v116, v24, v90
	v_fmac_f32_e32 v116, v25, v91
	v_add_f32_e32 v121, v121, v116
	v_mul_f32_e32 v116, v27, v93
	v_fmac_f32_e32 v116, v26, v92
	v_fmac_f32_e32 v116, v28, v94
	v_fmac_f32_e32 v116, v29, v95
	v_add_f32_e32 v121, v121, v116
	v_mul_f32_e32 v116, v31, v97
	v_fmac_f32_e32 v116, v30, v96
	v_fmac_f32_e32 v116, v32, v98
	v_fmac_f32_e32 v116, v33, v99
	v_add_f32_e32 v121, v121, v116
	v_min_f32_e32 v117, 0, v121
	v_mul_f32_e64 v118, |v121|, s16
	v_exp_f32_e32 v118, v118
	s_nop 0
	v_add_f32_e32 v118, 1.0, v118
	v_log_f32_e32 v118, v118
	s_nop 0
	v_mul_f32_e32 v119, 0x3f317217, v118
	v_fma_f32 v119, v118, s55, -v119
	v_fmac_f32_e32 v119, 0x3377d1cf, v118
	v_fmac_f32_e32 v119, 0x3f317217, v118
	v_sub_f32_e32 v121, v117, v119
	v_mul_f32_e32 v131, 0x3d800000, v121
	ds_write_b32 v50, v131 offset:0
	v_add_f32_e32 v130, v130, v131
	ds_read_b128 v[84:87], v49 offset:320
	ds_read_b128 v[88:91], v49 offset:336
	ds_read_b128 v[92:95], v49 offset:352
	ds_read_b128 v[96:99], v49 offset:368
	s_waitcnt lgkmcnt(4)
	v_mul_f32_e32 v116, v19, v101
	v_fmac_f32_e32 v116, v18, v100
	v_fmac_f32_e32 v116, v20, v102
	v_fmac_f32_e32 v116, v21, v103
	v_add_f32_e32 v121, v35, v116
	v_mul_f32_e32 v116, v23, v105
	v_fmac_f32_e32 v116, v22, v104
	v_fmac_f32_e32 v116, v24, v106
	v_fmac_f32_e32 v116, v25, v107
	v_add_f32_e32 v121, v121, v116
	v_mul_f32_e32 v116, v27, v109
	v_fmac_f32_e32 v116, v26, v108
	v_fmac_f32_e32 v116, v28, v110
	v_fmac_f32_e32 v116, v29, v111
	v_add_f32_e32 v121, v121, v116
	v_mul_f32_e32 v116, v31, v113
	v_fmac_f32_e32 v116, v30, v112
	v_fmac_f32_e32 v116, v32, v114
	v_fmac_f32_e32 v116, v33, v115
	v_add_f32_e32 v121, v121, v116
	v_min_f32_e32 v117, 0, v121
	v_mul_f32_e64 v118, |v121|, s16
	v_exp_f32_e32 v118, v118
	s_nop 0
	v_add_f32_e32 v118, 1.0, v118
	v_log_f32_e32 v118, v118
	s_nop 0
	v_mul_f32_e32 v119, 0x3f317217, v118
	v_fma_f32 v119, v118, s55, -v119
	v_fmac_f32_e32 v119, 0x3377d1cf, v118
	v_fmac_f32_e32 v119, 0x3f317217, v118
	v_sub_f32_e32 v121, v117, v119
	v_mul_f32_e32 v131, 0x3d800000, v121
	ds_write_b32 v50, v131 offset:2048
	v_add_f32_e32 v130, v130, v131
	ds_read_b128 v[100:103], v49 offset:448
	ds_read_b128 v[104:107], v49 offset:464
	ds_read_b128 v[108:111], v49 offset:480
	ds_read_b128 v[112:115], v49 offset:496
	s_waitcnt lgkmcnt(4)
	v_mul_f32_e32 v116, v19, v85
	v_fmac_f32_e32 v116, v18, v84
	v_fmac_f32_e32 v116, v20, v86
	v_fmac_f32_e32 v116, v21, v87
	v_add_f32_e32 v121, v35, v116
	v_mul_f32_e32 v116, v23, v89
	v_fmac_f32_e32 v116, v22, v88
	v_fmac_f32_e32 v116, v24, v90
	v_fmac_f32_e32 v116, v25, v91
	v_add_f32_e32 v121, v121, v116
	v_mul_f32_e32 v116, v27, v93
	v_fmac_f32_e32 v116, v26, v92
	v_fmac_f32_e32 v116, v28, v94
	v_fmac_f32_e32 v116, v29, v95
	v_add_f32_e32 v121, v121, v116
	v_mul_f32_e32 v116, v31, v97
	v_fmac_f32_e32 v116, v30, v96
	v_fmac_f32_e32 v116, v32, v98
	v_fmac_f32_e32 v116, v33, v99
	v_add_f32_e32 v121, v121, v116
	v_min_f32_e32 v117, 0, v121
	v_mul_f32_e64 v118, |v121|, s16
	v_exp_f32_e32 v118, v118
	s_nop 0
	v_add_f32_e32 v118, 1.0, v118
	v_log_f32_e32 v118, v118
	s_nop 0
	v_mul_f32_e32 v119, 0x3f317217, v118
	v_fma_f32 v119, v118, s55, -v119
	v_fmac_f32_e32 v119, 0x3377d1cf, v118
	v_fmac_f32_e32 v119, 0x3f317217, v118
	v_sub_f32_e32 v121, v117, v119
	v_mul_f32_e32 v131, 0x3d800000, v121
	ds_write_b32 v50, v131 offset:4096
	v_add_f32_e32 v130, v130, v131
	ds_read_b128 v[84:87], v49 offset:576
	ds_read_b128 v[88:91], v49 offset:592
	ds_read_b128 v[92:95], v49 offset:608
	ds_read_b128 v[96:99], v49 offset:624
	s_waitcnt lgkmcnt(4)
	v_mul_f32_e32 v116, v19, v101
	v_fmac_f32_e32 v116, v18, v100
	v_fmac_f32_e32 v116, v20, v102
	v_fmac_f32_e32 v116, v21, v103
	v_add_f32_e32 v121, v35, v116
	v_mul_f32_e32 v116, v23, v105
	v_fmac_f32_e32 v116, v22, v104
	v_fmac_f32_e32 v116, v24, v106
	v_fmac_f32_e32 v116, v25, v107
	v_add_f32_e32 v121, v121, v116
	v_mul_f32_e32 v116, v27, v109
	v_fmac_f32_e32 v116, v26, v108
	v_fmac_f32_e32 v116, v28, v110
	v_fmac_f32_e32 v116, v29, v111
	v_add_f32_e32 v121, v121, v116
	v_mul_f32_e32 v116, v31, v113
	v_fmac_f32_e32 v116, v30, v112
	v_fmac_f32_e32 v116, v32, v114
	v_fmac_f32_e32 v116, v33, v115
	v_add_f32_e32 v121, v121, v116
	v_min_f32_e32 v117, 0, v121
	v_mul_f32_e64 v118, |v121|, s16
	v_exp_f32_e32 v118, v118
	s_nop 0
	v_add_f32_e32 v118, 1.0, v118
	v_log_f32_e32 v118, v118
	s_nop 0
	v_mul_f32_e32 v119, 0x3f317217, v118
	v_fma_f32 v119, v118, s55, -v119
	v_fmac_f32_e32 v119, 0x3377d1cf, v118
	v_fmac_f32_e32 v119, 0x3f317217, v118
	v_sub_f32_e32 v121, v117, v119
	v_mul_f32_e32 v131, 0x3d800000, v121
	ds_write_b32 v50, v131 offset:6144
	v_add_f32_e32 v130, v130, v131
	ds_read_b128 v[100:103], v49 offset:704
	ds_read_b128 v[104:107], v49 offset:720
	ds_read_b128 v[108:111], v49 offset:736
	ds_read_b128 v[112:115], v49 offset:752
	s_waitcnt lgkmcnt(4)
; #define LAS __attribute__((address_space(3)))
; DI float logsig16(float z) { return (fminf(z, 0.f) - __logf(1.0f + __expf(-fabsf(z)))) * (1.0f / 16.0f); }
; DI void gla_gate_phase(const Params& P, LAS unsigned char* lds, int lj) {
;     ...
;     float lsb[64]; float totb = 0.f;
; #pragma unroll
;     for (int i = 0; i < 64; ++i) {
;       float z = bb_;
; #pragma unroll
;       for (int j4 = 0; j4 < 4; ++j4) { const f32x4 zz = *(const LAS f32x4*)(zL + i * 32 + 16 + j4 * 4); z += zz[0] * wb[j4 * 4] + zz[1] * wb[j4 * 4 + 1] + zz[2] * wb[j4 * 4 + 2] + zz[3] * wb[j4 * 4 + 3]; }
;       lsb[i] = logsig16(z); totb += lsb[i];
;     }
;     float runf = 0.f, runb = 0.f;
; #pragma unroll
;     for (int ib = 0; ib < 4; ++ib) {
;       bf16_t qraw[16], kraw[16];
; #pragma unroll
;       for (int ii = 0; ii < 16; ++ii) { const bf16_t* pr = proj + ((size_t)item * 64 + ib * 16 + ii) * 3072 + col; qraw[ii] = pr[0]; kraw[ii] = pr[512]; }
;       asm volatile("" ::: "memory");
; #pragma unroll
;       for (int ii = 0; ii < 16; ++ii) {
;         const int i = ib * 16 + ii;
;         float z = bf_;
; #pragma unroll
;         for (int j4 = 0; j4 < 4; ++j4) { const f32x4 zz = *(const LAS f32x4*)(zL + i * 32 + j4 * 4); z += zz[0] * wf[j4 * 4] + zz[1] * wf[j4 * 4 + 1] + zz[2] * wf[j4 * 4 + 2] + zz[3] * wf[j4 * 4 + 3]; }
	v_mul_f32_e32 v116, v19, v85
	v_fmac_f32_e32 v116, v18, v84
	v_fmac_f32_e32 v116, v20, v86
	v_fmac_f32_e32 v116, v21, v87
	v_add_f32_e32 v121, v35, v116
	v_mul_f32_e32 v116, v23, v89
	v_fmac_f32_e32 v116, v22, v88
	v_fmac_f32_e32 v116, v24, v90
	v_fmac_f32_e32 v116, v25, v91
	v_add_f32_e32 v121, v121, v116
	v_mul_f32_e32 v116, v27, v93
	v_fmac_f32_e32 v116, v26, v92
	v_fmac_f32_e32 v116, v28, v94
	v_fmac_f32_e32 v116, v29, v95
	v_add_f32_e32 v121, v121, v116
	v_mul_f32_e32 v116, v31, v97
	v_fmac_f32_e32 v116, v30, v96
	v_fmac_f32_e32 v116, v32, v98
	v_fmac_f32_e32 v116, v33, v99
	v_add_f32_e32 v121, v121, v116
	v_min_f32_e32 v117, 0, v121
	v_mul_f32_e64 v118, |v121|, s16
	v_exp_f32_e32 v118, v118
	s_nop 0
	v_add_f32_e32 v118, 1.0, v118
	v_log_f32_e32 v118, v118
	s_nop 0
	v_mul_f32_e32 v119, 0x3f317217, v118
	v_fma_f32 v119, v118, s55, -v119
	v_fmac_f32_e32 v119, 0x3377d1cf, v118
	v_fmac_f32_e32 v119, 0x3f317217, v118
	v_sub_f32_e32 v121, v117, v119
	v_mul_f32_e32 v131, 0x3d800000, v121
	ds_write_b32 v50, v131 offset:8192
	v_add_f32_e32 v130, v130, v131
	ds_read_b128 v[84:87], v49 offset:832
	ds_read_b128 v[88:91], v49 offset:848
	ds_read_b128 v[92:95], v49 offset:864
	ds_read_b128 v[96:99], v49 offset:880
	s_waitcnt lgkmcnt(4)
	v_mul_f32_e32 v116, v19, v101
	v_fmac_f32_e32 v116, v18, v100
	v_fmac_f32_e32 v116, v20, v102
	v_fmac_f32_e32 v116, v21, v103
	v_add_f32_e32 v121, v35, v116
	v_mul_f32_e32 v116, v23, v105
	v_fmac_f32_e32 v116, v22, v104
	v_fmac_f32_e32 v116, v24, v106
	v_fmac_f32_e32 v116, v25, v107
	v_add_f32_e32 v121, v121, v116
	v_mul_f32_e32 v116, v27, v109
	v_fmac_f32_e32 v116, v26, v108
	v_fmac_f32_e32 v116, v28, v110
	v_fmac_f32_e32 v116, v29, v111
	v_add_f32_e32 v121, v121, v116
	v_mul_f32_e32 v116, v31, v113
	v_fmac_f32_e32 v116, v30, v112
	v_fmac_f32_e32 v116, v32, v114
	v_fmac_f32_e32 v116, v33, v115
	v_add_f32_e32 v121, v121, v116
	v_min_f32_e32 v117, 0, v121
	v_mul_f32_e64 v118, |v121|, s16
	v_exp_f32_e32 v118, v118
	s_nop 0
	v_add_f32_e32 v118, 1.0, v118
	v_log_f32_e32 v118, v118
	s_nop 0
	v_mul_f32_e32 v119, 0x3f317217, v118
	v_fma_f32 v119, v118, s55, -v119
	v_fmac_f32_e32 v119, 0x3377d1cf, v118
	v_fmac_f32_e32 v119, 0x3f317217, v118
	v_sub_f32_e32 v121, v117, v119
	v_mul_f32_e32 v131, 0x3d800000, v121
	ds_write_b32 v50, v131 offset:10240
	v_add_f32_e32 v130, v130, v131
	ds_read_b128 v[100:103], v49 offset:960
	ds_read_b128 v[104:107], v49 offset:976
	ds_read_b128 v[108:111], v49 offset:992
	ds_read_b128 v[112:115], v49 offset:1008
	s_waitcnt lgkmcnt(4)
	v_mul_f32_e32 v116, v19, v85
	v_fmac_f32_e32 v116, v18, v84
	v_fmac_f32_e32 v116, v20, v86
	v_fmac_f32_e32 v116, v21, v87
	v_add_f32_e32 v121, v35, v116
	v_mul_f32_e32 v116, v23, v89
	v_fmac_f32_e32 v116, v22, v88
	v_fmac_f32_e32 v116, v24, v90
	v_fmac_f32_e32 v116, v25, v91
	v_add_f32_e32 v121, v121, v116
	v_mul_f32_e32 v116, v27, v93
	v_fmac_f32_e32 v116, v26, v92
	v_fmac_f32_e32 v116, v28, v94
	v_fmac_f32_e32 v116, v29, v95
	v_add_f32_e32 v121, v121, v116
	v_mul_f32_e32 v116, v31, v97
	v_fmac_f32_e32 v116, v30, v96
	v_fmac_f32_e32 v116, v32, v98
	v_fmac_f32_e32 v116, v33, v99
	v_add_f32_e32 v121, v121, v116
	v_min_f32_e32 v117, 0, v121
	v_mul_f32_e64 v118, |v121|, s16
	v_exp_f32_e32 v118, v118
	s_nop 0
	v_add_f32_e32 v118, 1.0, v118
	v_log_f32_e32 v118, v118
	s_nop 0
	v_mul_f32_e32 v119, 0x3f317217, v118
	v_fma_f32 v119, v118, s55, -v119
	v_fmac_f32_e32 v119, 0x3377d1cf, v118
	v_fmac_f32_e32 v119, 0x3f317217, v118
	v_sub_f32_e32 v121, v117, v119
	v_mul_f32_e32 v131, 0x3d800000, v121
	ds_write_b32 v50, v131 offset:12288
	v_add_f32_e32 v130, v130, v131
	v_add_u32_e32 v49, 0x400, v49
	ds_read_b128 v[84:87], v49 offset:64
	ds_read_b128 v[88:91], v49 offset:80
	ds_read_b128 v[92:95], v49 offset:96
	ds_read_b128 v[96:99], v49 offset:112
	s_waitcnt lgkmcnt(4)
	v_mul_f32_e32 v116, v19, v101
	v_fmac_f32_e32 v116, v18, v100
	v_fmac_f32_e32 v116, v20, v102
	v_fmac_f32_e32 v116, v21, v103
	v_add_f32_e32 v121, v35, v116
	v_mul_f32_e32 v116, v23, v105
	v_fmac_f32_e32 v116, v22, v104
	v_fmac_f32_e32 v116, v24, v106
	v_fmac_f32_e32 v116, v25, v107
	v_add_f32_e32 v121, v121, v116
	v_mul_f32_e32 v116, v27, v109
	v_fmac_f32_e32 v116, v26, v108
	v_fmac_f32_e32 v116, v28, v110
	v_fmac_f32_e32 v116, v29, v111
	v_add_f32_e32 v121, v121, v116
	v_mul_f32_e32 v116, v31, v113
	v_fmac_f32_e32 v116, v30, v112
	v_fmac_f32_e32 v116, v32, v114
	v_fmac_f32_e32 v116, v33, v115
	v_add_f32_e32 v121, v121, v116
	v_min_f32_e32 v117, 0, v121
	v_mul_f32_e64 v118, |v121|, s16
	v_exp_f32_e32 v118, v118
	s_nop 0
	v_add_f32_e32 v118, 1.0, v118
	v_log_f32_e32 v118, v118
	s_nop 0
	v_mul_f32_e32 v119, 0x3f317217, v118
	v_fma_f32 v119, v118, s55, -v119
	v_fmac_f32_e32 v119, 0x3377d1cf, v118
	v_fmac_f32_e32 v119, 0x3f317217, v118
	v_sub_f32_e32 v121, v117, v119
	v_mul_f32_e32 v131, 0x3d800000, v121
	ds_write_b32 v50, v131 offset:14336
	v_add_f32_e32 v130, v130, v131
	v_add_u32_e32 v50, 0x4000, v50
	s_add_i32 s43, s43, 1
	s_cmp_lt_u32 s43, 8
	s_cbranch_scc1 .Lgt_pre
	s_waitcnt lgkmcnt(0)
	v_mov_b32_e32 v128, 0
	v_mov_b32_e32 v129, 0
	v_mov_b32_e32 v49, 0
	v_add_u32_e32 v50, 0x2000, v36
	ds_read_b128 v[84:87], v49 offset:0
	ds_read_b128 v[88:91], v49 offset:16
	ds_read_b128 v[92:95], v49 offset:32
	ds_read_b128 v[96:99], v49 offset:48
	s_mov_b32 s43, 0
.Lgt_main:
	s_cmp_eq_u32 s43, 0
	s_cbranch_scc1 .Lgt_w0
	s_waitcnt vmcnt(32)
	s_branch .Lgt_w1

; #define LAS __attribute__((address_space(3)))
; DI float bf2f(bf16_t v) { return __uint_as_float(((unsigned)v) << 16); }
; DI bf16_t f2bf(float f) { return (bf16_t)(cvt_pk(f, 0.f) & 0xffffu); }
; DI float logsig16(float z) { return (fminf(z, 0.f) - __logf(1.0f + __expf(-fabsf(z)))) * (1.0f / 16.0f); }
; DI void gla_gate_phase(const Params& P, LAS unsigned char* lds, int lj) {
;     ...
;     for (int ib = 0; ib < 4; ++ib) {
;       bf16_t qraw[16], kraw[16];
; #pragma unroll
;       for (int ii = 0; ii < 16; ++ii) { const bf16_t* pr = proj + ((size_t)item * 64 + ib * 16 + ii) * 3072 + col; qraw[ii] = pr[0]; kraw[ii] = pr[512]; }
;       asm volatile("" ::: "memory");
; #pragma unroll
;       for (int ii = 0; ii < 16; ++ii) {
;         const int i = ib * 16 + ii;
;         float z = bf_;
; #pragma unroll
;         for (int j4 = 0; j4 < 4; ++j4) { const f32x4 zz = *(const LAS f32x4*)(zL + i * 32 + j4 * 4); z += zz[0] * wf[j4 * 4] + zz[1] * wf[j4 * 4 + 1] + zz[2] * wf[j4 * 4 + 2] + zz[3] * wf[j4 * 4 + 3]; }
;         runf += logsig16(z);
;         const float Bi = totb - runb; runb += lsb[i];
;         const size_t tokrow = (size_t)item * 64 + i;
;         bf16_t* pr = proj + tokrow * 3072 + col;
;         const float q = bf2f(qraw[ii]), k = bf2f(kraw[ii]);
;         pr[0] = f2bf(q * __expf(runf)); pr[512] = f2bf(k * __expf(-runf));
;         QB[tokrow * 512 + col] = f2bf(q * __expf(Bi)); KB[tokrow * 512 + col] = f2bf(k * __expf(-Bi));
;       }
.Lgt_w1:
	v_lshlrev_b32_e32 v68, 16, v52
	v_lshlrev_b32_e32 v76, 16, v60
	v_lshlrev_b32_e32 v69, 16, v53
	v_lshlrev_b32_e32 v77, 16, v61
	v_lshlrev_b32_e32 v70, 16, v54
	v_lshlrev_b32_e32 v78, 16, v62
	v_lshlrev_b32_e32 v71, 16, v55
	v_lshlrev_b32_e32 v79, 16, v63
	v_lshlrev_b32_e32 v72, 16, v56
	v_lshlrev_b32_e32 v80, 16, v64
	v_lshlrev_b32_e32 v73, 16, v57
	v_lshlrev_b32_e32 v81, 16, v65
	v_lshlrev_b32_e32 v74, 16, v58
	v_lshlrev_b32_e32 v82, 16, v66
	v_lshlrev_b32_e32 v75, 16, v59
	v_lshlrev_b32_e32 v83, 16, v67
	s_cmp_eq_u32 s43, 7
	s_cbranch_scc1 .Lgt_nold
	s_add_u32 s20, s46, 0xc000
	s_addc_u32 s21, s47, 0
	global_load_ushort v52, v38, s[20:21]
	global_load_ushort v60, v38, s[20:21] offset:1024
	global_load_ushort v53, v39, s[20:21]
	global_load_ushort v61, v39, s[20:21] offset:1024
	global_load_ushort v54, v40, s[20:21]
	global_load_ushort v62, v40, s[20:21] offset:1024
	global_load_ushort v55, v41, s[20:21]
	global_load_ushort v63, v41, s[20:21] offset:1024
	global_load_ushort v56, v42, s[20:21]
	global_load_ushort v64, v42, s[20:21] offset:1024
	global_load_ushort v57, v43, s[20:21]
	global_load_ushort v65, v43, s[20:21] offset:1024
	global_load_ushort v58, v44, s[20:21]
	global_load_ushort v66, v44, s[20:21] offset:1024
	global_load_ushort v59, v45, s[20:21]
	global_load_ushort v67, v45, s[20:21] offset:1024
.Lgt_nold:
	ds_read_b32 v131, v50 offset:0
	ds_read_b128 v[100:103], v49 offset:128
	ds_read_b128 v[104:107], v49 offset:144
	ds_read_b128 v[108:111], v49 offset:160
	ds_read_b128 v[112:115], v49 offset:176
	s_waitcnt lgkmcnt(5)
	v_mul_f32_e32 v116, v3, v85
	v_fmac_f32_e32 v116, v2, v84
	v_fmac_f32_e32 v116, v4, v86
	v_fmac_f32_e32 v116, v5, v87
	v_add_f32_e32 v121, v34, v116
	v_mul_f32_e32 v116, v7, v89
	v_fmac_f32_e32 v116, v6, v88
	v_fmac_f32_e32 v116, v8, v90
	v_fmac_f32_e32 v116, v9, v91
	v_add_f32_e32 v121, v121, v116
	v_mul_f32_e32 v116, v11, v93
	v_fmac_f32_e32 v116, v10, v92
	v_fmac_f32_e32 v116, v12, v94
	v_fmac_f32_e32 v116, v13, v95
	v_add_f32_e32 v121, v121, v116
	v_mul_f32_e32 v116, v15, v97
	v_fmac_f32_e32 v116, v14, v96
	v_fmac_f32_e32 v116, v16, v98
	v_fmac_f32_e32 v116, v17, v99
	v_add_f32_e32 v121, v121, v116
	v_min_f32_e32 v117, 0, v121
	v_mul_f32_e64 v118, |v121|, s16
	v_exp_f32_e32 v118, v118
	s_nop 0
	v_add_f32_e32 v118, 1.0, v118
	v_log_f32_e32 v118, v118
	s_nop 0
	v_mul_f32_e32 v119, 0x3f317217, v118
	v_fma_f32 v119, v118, s55, -v119
	v_fmac_f32_e32 v119, 0x3377d1cf, v118
	v_fmac_f32_e32 v119, 0x3f317217, v118
	v_sub_f32_e32 v121, v117, v119
	v_fmac_f32_e32 v128, 0x3d800000, v121
	v_sub_f32_e32 v121, v130, v129
	s_waitcnt lgkmcnt(4)
	v_add_f32_e32 v129, v129, v131
	v_mul_f32_e32 v120, 0x3fb8aa3b, v128
	v_exp_f32_e32 v120, v120
	s_nop 0
	v_mul_f32_e32 v120, v120, v68
	v_cvt_pk_bf16_f32 v120, v120, v1
	global_store_short v38, v120, s[46:47]
	v_mul_f32_e32 v120, 0xbfb8aa3b, v128
	v_exp_f32_e32 v120, v120
	s_nop 0
	v_mul_f32_e32 v120, v120, v76
	v_cvt_pk_bf16_f32 v120, v120, v1
	global_store_short v38, v120, s[46:47] offset:1024
	v_mul_f32_e32 v120, 0x3fb8aa3b, v121
	v_exp_f32_e32 v120, v120
	s_nop 0
	v_mul_f32_e32 v120, v120, v68
	v_cvt_pk_bf16_f32 v120, v120, v1
	global_store_short v37, v120, s[48:49]
	v_mul_f32_e32 v120, 0xbfb8aa3b, v121
	v_exp_f32_e32 v120, v120
	s_nop 0
	v_mul_f32_e32 v120, v120, v76
	v_cvt_pk_bf16_f32 v120, v120, v1
	global_store_short v37, v120, s[50:51]
	ds_read_b32 v131, v50 offset:2048
	ds_read_b128 v[84:87], v49 offset:256
	ds_read_b128 v[88:91], v49 offset:272
	ds_read_b128 v[92:95], v49 offset:288
	ds_read_b128 v[96:99], v49 offset:304
	s_waitcnt lgkmcnt(5)
	v_mul_f32_e32 v116, v3, v101
	v_fmac_f32_e32 v116, v2, v100
	v_fmac_f32_e32 v116, v4, v102
	v_fmac_f32_e32 v116, v5, v103
	v_add_f32_e32 v121, v34, v116
	v_mul_f32_e32 v116, v7, v105
	v_fmac_f32_e32 v116, v6, v104
	v_fmac_f32_e32 v116, v8, v106
	v_fmac_f32_e32 v116, v9, v107
	v_add_f32_e32 v121, v121, v116
	v_mul_f32_e32 v116, v11, v109
	v_fmac_f32_e32 v116, v10, v108
	v_fmac_f32_e32 v116, v12, v110
	v_fmac_f32_e32 v116, v13, v111
	v_add_f32_e32 v121, v121, v116
	v_mul_f32_e32 v116, v15, v113
	v_fmac_f32_e32 v116, v14, v112
	v_fmac_f32_e32 v116, v16, v114
	v_fmac_f32_e32 v116, v17, v115
	v_add_f32_e32 v121, v121, v116
	v_min_f32_e32 v117, 0, v121
	v_mul_f32_e64 v118, |v121|, s16
	v_exp_f32_e32 v118, v118
	s_nop 0
	v_add_f32_e32 v118, 1.0, v118
	v_log_f32_e32 v118, v118
	s_nop 0
	v_mul_f32_e32 v119, 0x3f317217, v118
	v_fma_f32 v119, v118, s55, -v119
	v_fmac_f32_e32 v119, 0x3377d1cf, v118
	v_fmac_f32_e32 v119, 0x3f317217, v118
	v_sub_f32_e32 v121, v117, v119
	v_fmac_f32_e32 v128, 0x3d800000, v121
	v_sub_f32_e32 v121, v130, v129
	s_waitcnt lgkmcnt(4)
	v_add_f32_e32 v129, v129, v131
	v_mul_f32_e32 v120, 0x3fb8aa3b, v128
	v_exp_f32_e32 v120, v120
	s_nop 0
	v_mul_f32_e32 v120, v120, v69
	v_cvt_pk_bf16_f32 v120, v120, v1
	global_store_short v39, v120, s[46:47]
	v_mul_f32_e32 v120, 0xbfb8aa3b, v128
	v_exp_f32_e32 v120, v120
	s_nop 0
	v_mul_f32_e32 v120, v120, v77
	v_cvt_pk_bf16_f32 v120, v120, v1
	global_store_short v39, v120, s[46:47] offset:1024
	v_mul_f32_e32 v120, 0x3fb8aa3b, v121
	v_exp_f32_e32 v120, v120
	s_nop 0
	v_mul_f32_e32 v120, v120, v69
	v_cvt_pk_bf16_f32 v120, v120, v1
	global_store_short v37, v120, s[48:49] offset:1024
	v_mul_f32_e32 v120, 0xbfb8aa3b, v121
	v_exp_f32_e32 v120, v120
	s_nop 0
	v_mul_f32_e32 v120, v120, v77
	v_cvt_pk_bf16_f32 v120, v120, v1
	global_store_short v37, v120, s[50:51] offset:1024
	ds_read_b32 v131, v50 offset:4096
	ds_read_b128 v[100:103], v49 offset:384
	ds_read_b128 v[104:107], v49 offset:400
	ds_read_b128 v[108:111], v49 offset:416
	ds_read_b128 v[112:115], v49 offset:432
	s_waitcnt lgkmcnt(5)
; #define LAS __attribute__((address_space(3)))
; DI float bf2f(bf16_t v) { return __uint_as_float(((unsigned)v) << 16); }
; DI bf16_t f2bf(float f) { return (bf16_t)(cvt_pk(f, 0.f) & 0xffffu); }
; DI float logsig16(float z) { return (fminf(z, 0.f) - __logf(1.0f + __expf(-fabsf(z)))) * (1.0f / 16.0f); }
; DI void gla_gate_phase(const Params& P, LAS unsigned char* lds, int lj) {
;     ...
;       for (int ii = 0; ii < 16; ++ii) {
;         const int i = ib * 16 + ii;
;         float z = bf_;
; #pragma unroll
;         for (int j4 = 0; j4 < 4; ++j4) { const f32x4 zz = *(const LAS f32x4*)(zL + i * 32 + j4 * 4); z += zz[0] * wf[j4 * 4] + zz[1] * wf[j4 * 4 + 1] + zz[2] * wf[j4 * 4 + 2] + zz[3] * wf[j4 * 4 + 3]; }
;         runf += logsig16(z);
;         const float Bi = totb - runb; runb += lsb[i];
;         const size_t tokrow = (size_t)item * 64 + i;
;         bf16_t* pr = proj + tokrow * 3072 + col;
;         const float q = bf2f(qraw[ii]), k = bf2f(kraw[ii]);
;         pr[0] = f2bf(q * __expf(runf)); pr[512] = f2bf(k * __expf(-runf));
;         QB[tokrow * 512 + col] = f2bf(q * __expf(Bi)); KB[tokrow * 512 + col] = f2bf(k * __expf(-Bi));
;       }
	v_mul_f32_e32 v116, v3, v85
	v_fmac_f32_e32 v116, v2, v84
	v_fmac_f32_e32 v116, v4, v86
	v_fmac_f32_e32 v116, v5, v87
	v_add_f32_e32 v121, v34, v116
	v_mul_f32_e32 v116, v7, v89
	v_fmac_f32_e32 v116, v6, v88
	v_fmac_f32_e32 v116, v8, v90
	v_fmac_f32_e32 v116, v9, v91
	v_add_f32_e32 v121, v121, v116
	v_mul_f32_e32 v116, v11, v93
	v_fmac_f32_e32 v116, v10, v92
	v_fmac_f32_e32 v116, v12, v94
	v_fmac_f32_e32 v116, v13, v95
	v_add_f32_e32 v121, v121, v116
	v_mul_f32_e32 v116, v15, v97
	v_fmac_f32_e32 v116, v14, v96
	v_fmac_f32_e32 v116, v16, v98
	v_fmac_f32_e32 v116, v17, v99
	v_add_f32_e32 v121, v121, v116
	v_min_f32_e32 v117, 0, v121
	v_mul_f32_e64 v118, |v121|, s16
	v_exp_f32_e32 v118, v118
	s_nop 0
	v_add_f32_e32 v118, 1.0, v118
	v_log_f32_e32 v118, v118
	s_nop 0
	v_mul_f32_e32 v119, 0x3f317217, v118
	v_fma_f32 v119, v118, s55, -v119
	v_fmac_f32_e32 v119, 0x3377d1cf, v118
	v_fmac_f32_e32 v119, 0x3f317217, v118
	v_sub_f32_e32 v121, v117, v119
	v_fmac_f32_e32 v128, 0x3d800000, v121
	v_sub_f32_e32 v121, v130, v129
	s_waitcnt lgkmcnt(4)
	v_add_f32_e32 v129, v129, v131
	v_mul_f32_e32 v120, 0x3fb8aa3b, v128
	v_exp_f32_e32 v120, v120
	s_nop 0
	v_mul_f32_e32 v120, v120, v70
	v_cvt_pk_bf16_f32 v120, v120, v1
	global_store_short v40, v120, s[46:47]
	v_mul_f32_e32 v120, 0xbfb8aa3b, v128
	v_exp_f32_e32 v120, v120
	s_nop 0
	v_mul_f32_e32 v120, v120, v78
	v_cvt_pk_bf16_f32 v120, v120, v1
	global_store_short v40, v120, s[46:47] offset:1024
	v_mul_f32_e32 v120, 0x3fb8aa3b, v121
	v_exp_f32_e32 v120, v120
	s_nop 0
	v_mul_f32_e32 v120, v120, v70
	v_cvt_pk_bf16_f32 v120, v120, v1
	global_store_short v37, v120, s[48:49] offset:2048
	v_mul_f32_e32 v120, 0xbfb8aa3b, v121
	v_exp_f32_e32 v120, v120
	s_nop 0
	v_mul_f32_e32 v120, v120, v78
	v_cvt_pk_bf16_f32 v120, v120, v1
	global_store_short v37, v120, s[50:51] offset:2048
	ds_read_b32 v131, v50 offset:6144
	ds_read_b128 v[84:87], v49 offset:512
	ds_read_b128 v[88:91], v49 offset:528
	ds_read_b128 v[92:95], v49 offset:544
	ds_read_b128 v[96:99], v49 offset:560
	s_waitcnt lgkmcnt(5)
	v_mul_f32_e32 v116, v3, v101
	v_fmac_f32_e32 v116, v2, v100
	v_fmac_f32_e32 v116, v4, v102
	v_fmac_f32_e32 v116, v5, v103
	v_add_f32_e32 v121, v34, v116
	v_mul_f32_e32 v116, v7, v105
	v_fmac_f32_e32 v116, v6, v104
	v_fmac_f32_e32 v116, v8, v106
	v_fmac_f32_e32 v116, v9, v107
	v_add_f32_e32 v121, v121, v116
	v_mul_f32_e32 v116, v11, v109
	v_fmac_f32_e32 v116, v10, v108
	v_fmac_f32_e32 v116, v12, v110
	v_fmac_f32_e32 v116, v13, v111
	v_add_f32_e32 v121, v121, v116
	v_mul_f32_e32 v116, v15, v113
	v_fmac_f32_e32 v116, v14, v112
	v_fmac_f32_e32 v116, v16, v114
	v_fmac_f32_e32 v116, v17, v115
	v_add_f32_e32 v121, v121, v116
	v_min_f32_e32 v117, 0, v121
	v_mul_f32_e64 v118, |v121|, s16
	v_exp_f32_e32 v118, v118
	s_nop 0
	v_add_f32_e32 v118, 1.0, v118
	v_log_f32_e32 v118, v118
	s_nop 0
	v_mul_f32_e32 v119, 0x3f317217, v118
	v_fma_f32 v119, v118, s55, -v119
	v_fmac_f32_e32 v119, 0x3377d1cf, v118
	v_fmac_f32_e32 v119, 0x3f317217, v118
	v_sub_f32_e32 v121, v117, v119
	v_fmac_f32_e32 v128, 0x3d800000, v121
	v_sub_f32_e32 v121, v130, v129
	s_waitcnt lgkmcnt(4)
	v_add_f32_e32 v129, v129, v131
	v_mul_f32_e32 v120, 0x3fb8aa3b, v128
	v_exp_f32_e32 v120, v120
	s_nop 0
	v_mul_f32_e32 v120, v120, v71
	v_cvt_pk_bf16_f32 v120, v120, v1
	global_store_short v41, v120, s[46:47]
	v_mul_f32_e32 v120, 0xbfb8aa3b, v128
	v_exp_f32_e32 v120, v120
	s_nop 0
	v_mul_f32_e32 v120, v120, v79
	v_cvt_pk_bf16_f32 v120, v120, v1
	global_store_short v41, v120, s[46:47] offset:1024
	v_mul_f32_e32 v120, 0x3fb8aa3b, v121
	v_exp_f32_e32 v120, v120
	s_nop 0
	v_mul_f32_e32 v120, v120, v71
	v_cvt_pk_bf16_f32 v120, v120, v1
	global_store_short v37, v120, s[48:49] offset:3072
	v_mul_f32_e32 v120, 0xbfb8aa3b, v121
	v_exp_f32_e32 v120, v120
	s_nop 0
	v_mul_f32_e32 v120, v120, v79
	v_cvt_pk_bf16_f32 v120, v120, v1
	global_store_short v37, v120, s[50:51] offset:3072
	ds_read_b32 v131, v50 offset:8192
	ds_read_b128 v[100:103], v49 offset:640
	ds_read_b128 v[104:107], v49 offset:656
	ds_read_b128 v[108:111], v49 offset:672
	ds_read_b128 v[112:115], v49 offset:688
	s_waitcnt lgkmcnt(5)
	v_mul_f32_e32 v116, v3, v85
	v_fmac_f32_e32 v116, v2, v84
	v_fmac_f32_e32 v116, v4, v86
	v_fmac_f32_e32 v116, v5, v87
	v_add_f32_e32 v121, v34, v116
	v_mul_f32_e32 v116, v7, v89
	v_fmac_f32_e32 v116, v6, v88
	v_fmac_f32_e32 v116, v8, v90
	v_fmac_f32_e32 v116, v9, v91
	v_add_f32_e32 v121, v121, v116
	v_mul_f32_e32 v116, v11, v93
	v_fmac_f32_e32 v116, v10, v92
	v_fmac_f32_e32 v116, v12, v94
	v_fmac_f32_e32 v116, v13, v95
	v_add_f32_e32 v121, v121, v116
	v_mul_f32_e32 v116, v15, v97
	v_fmac_f32_e32 v116, v14, v96
	v_fmac_f32_e32 v116, v16, v98
	v_fmac_f32_e32 v116, v17, v99
	v_add_f32_e32 v121, v121, v116
	v_min_f32_e32 v117, 0, v121
	v_mul_f32_e64 v118, |v121|, s16
	v_exp_f32_e32 v118, v118
	s_nop 0
	v_add_f32_e32 v118, 1.0, v118
	v_log_f32_e32 v118, v118
	s_nop 0
	v_mul_f32_e32 v119, 0x3f317217, v118
	v_fma_f32 v119, v118, s55, -v119
	v_fmac_f32_e32 v119, 0x3377d1cf, v118
	v_fmac_f32_e32 v119, 0x3f317217, v118
	v_sub_f32_e32 v121, v117, v119
	v_fmac_f32_e32 v128, 0x3d800000, v121
	v_sub_f32_e32 v121, v130, v129
	s_waitcnt lgkmcnt(4)
; #define LAS __attribute__((address_space(3)))
; DI float bf2f(bf16_t v) { return __uint_as_float(((unsigned)v) << 16); }
; DI bf16_t f2bf(float f) { return (bf16_t)(cvt_pk(f, 0.f) & 0xffffu); }
; DI float logsig16(float z) { return (fminf(z, 0.f) - __logf(1.0f + __expf(-fabsf(z)))) * (1.0f / 16.0f); }
; DI void gla_gate_phase(const Params& P, LAS unsigned char* lds, int lj) {
;     ...
;       for (int ii = 0; ii < 16; ++ii) {
;         const int i = ib * 16 + ii;
;         float z = bf_;
; #pragma unroll
;         for (int j4 = 0; j4 < 4; ++j4) { const f32x4 zz = *(const LAS f32x4*)(zL + i * 32 + j4 * 4); z += zz[0] * wf[j4 * 4] + zz[1] * wf[j4 * 4 + 1] + zz[2] * wf[j4 * 4 + 2] + zz[3] * wf[j4 * 4 + 3]; }
;         runf += logsig16(z);
;         const float Bi = totb - runb; runb += lsb[i];
;         const size_t tokrow = (size_t)item * 64 + i;
;         bf16_t* pr = proj + tokrow * 3072 + col;
;         const float q = bf2f(qraw[ii]), k = bf2f(kraw[ii]);
;         pr[0] = f2bf(q * __expf(runf)); pr[512] = f2bf(k * __expf(-runf));
;         QB[tokrow * 512 + col] = f2bf(q * __expf(Bi)); KB[tokrow * 512 + col] = f2bf(k * __expf(-Bi));
;       }
	v_add_f32_e32 v129, v129, v131
	v_mul_f32_e32 v120, 0x3fb8aa3b, v128
	v_exp_f32_e32 v120, v120
	s_nop 0
	v_mul_f32_e32 v120, v120, v72
	v_cvt_pk_bf16_f32 v120, v120, v1
	global_store_short v42, v120, s[46:47]
	v_mul_f32_e32 v120, 0xbfb8aa3b, v128
	v_exp_f32_e32 v120, v120
	s_nop 0
	v_mul_f32_e32 v120, v120, v80
	v_cvt_pk_bf16_f32 v120, v120, v1
	global_store_short v42, v120, s[46:47] offset:1024
	v_mul_f32_e32 v120, 0x3fb8aa3b, v121
	v_exp_f32_e32 v120, v120
	s_nop 0
	v_mul_f32_e32 v120, v120, v72
	v_cvt_pk_bf16_f32 v120, v120, v1
	global_store_short v46, v120, s[48:49]
	v_mul_f32_e32 v120, 0xbfb8aa3b, v121
	v_exp_f32_e32 v120, v120
	s_nop 0
	v_mul_f32_e32 v120, v120, v80
	v_cvt_pk_bf16_f32 v120, v120, v1
	global_store_short v46, v120, s[50:51]
	ds_read_b32 v131, v50 offset:10240
	ds_read_b128 v[84:87], v49 offset:768
	ds_read_b128 v[88:91], v49 offset:784
	ds_read_b128 v[92:95], v49 offset:800
	ds_read_b128 v[96:99], v49 offset:816
	s_waitcnt lgkmcnt(5)
	v_mul_f32_e32 v116, v3, v101
	v_fmac_f32_e32 v116, v2, v100
	v_fmac_f32_e32 v116, v4, v102
	v_fmac_f32_e32 v116, v5, v103
	v_add_f32_e32 v121, v34, v116
	v_mul_f32_e32 v116, v7, v105
	v_fmac_f32_e32 v116, v6, v104
	v_fmac_f32_e32 v116, v8, v106
	v_fmac_f32_e32 v116, v9, v107
	v_add_f32_e32 v121, v121, v116
	v_mul_f32_e32 v116, v11, v109
	v_fmac_f32_e32 v116, v10, v108
	v_fmac_f32_e32 v116, v12, v110
	v_fmac_f32_e32 v116, v13, v111
	v_add_f32_e32 v121, v121, v116
	v_mul_f32_e32 v116, v15, v113
	v_fmac_f32_e32 v116, v14, v112
	v_fmac_f32_e32 v116, v16, v114
	v_fmac_f32_e32 v116, v17, v115
	v_add_f32_e32 v121, v121, v116
	v_min_f32_e32 v117, 0, v121
	v_mul_f32_e64 v118, |v121|, s16
	v_exp_f32_e32 v118, v118
	s_nop 0
	v_add_f32_e32 v118, 1.0, v118
	v_log_f32_e32 v118, v118
	s_nop 0
	v_mul_f32_e32 v119, 0x3f317217, v118
	v_fma_f32 v119, v118, s55, -v119
	v_fmac_f32_e32 v119, 0x3377d1cf, v118
	v_fmac_f32_e32 v119, 0x3f317217, v118
	v_sub_f32_e32 v121, v117, v119
	v_fmac_f32_e32 v128, 0x3d800000, v121
	v_sub_f32_e32 v121, v130, v129
	s_waitcnt lgkmcnt(4)
	v_add_f32_e32 v129, v129, v131
	v_mul_f32_e32 v120, 0x3fb8aa3b, v128
	v_exp_f32_e32 v120, v120
	s_nop 0
	v_mul_f32_e32 v120, v120, v73
	v_cvt_pk_bf16_f32 v120, v120, v1
	global_store_short v43, v120, s[46:47]
	v_mul_f32_e32 v120, 0xbfb8aa3b, v128
	v_exp_f32_e32 v120, v120
	s_nop 0
	v_mul_f32_e32 v120, v120, v81
	v_cvt_pk_bf16_f32 v120, v120, v1
	global_store_short v43, v120, s[46:47] offset:1024
	v_mul_f32_e32 v120, 0x3fb8aa3b, v121
	v_exp_f32_e32 v120, v120
	s_nop 0
	v_mul_f32_e32 v120, v120, v73
	v_cvt_pk_bf16_f32 v120, v120, v1
	global_store_short v46, v120, s[48:49] offset:1024
	v_mul_f32_e32 v120, 0xbfb8aa3b, v121
	v_exp_f32_e32 v120, v120
	s_nop 0
	v_mul_f32_e32 v120, v120, v81
	v_cvt_pk_bf16_f32 v120, v120, v1
	global_store_short v46, v120, s[50:51] offset:1024
	ds_read_b32 v131, v50 offset:12288
	ds_read_b128 v[100:103], v49 offset:896
	ds_read_b128 v[104:107], v49 offset:912
	ds_read_b128 v[108:111], v49 offset:928
	ds_read_b128 v[112:115], v49 offset:944
	s_waitcnt lgkmcnt(5)
	v_mul_f32_e32 v116, v3, v85
	v_fmac_f32_e32 v116, v2, v84
	v_fmac_f32_e32 v116, v4, v86
	v_fmac_f32_e32 v116, v5, v87
	v_add_f32_e32 v121, v34, v116
	v_mul_f32_e32 v116, v7, v89
	v_fmac_f32_e32 v116, v6, v88
	v_fmac_f32_e32 v116, v8, v90
	v_fmac_f32_e32 v116, v9, v91
	v_add_f32_e32 v121, v121, v116
	v_mul_f32_e32 v116, v11, v93
	v_fmac_f32_e32 v116, v10, v92
	v_fmac_f32_e32 v116, v12, v94
	v_fmac_f32_e32 v116, v13, v95
	v_add_f32_e32 v121, v121, v116
	v_mul_f32_e32 v116, v15, v97
	v_fmac_f32_e32 v116, v14, v96
	v_fmac_f32_e32 v116, v16, v98
	v_fmac_f32_e32 v116, v17, v99
	v_add_f32_e32 v121, v121, v116
	v_min_f32_e32 v117, 0, v121
	v_mul_f32_e64 v118, |v121|, s16
	v_exp_f32_e32 v118, v118
	s_nop 0
	v_add_f32_e32 v118, 1.0, v118
	v_log_f32_e32 v118, v118
	s_nop 0
	v_mul_f32_e32 v119, 0x3f317217, v118
	v_fma_f32 v119, v118, s55, -v119
	v_fmac_f32_e32 v119, 0x3377d1cf, v118
	v_fmac_f32_e32 v119, 0x3f317217, v118
	v_sub_f32_e32 v121, v117, v119
	v_fmac_f32_e32 v128, 0x3d800000, v121
	v_sub_f32_e32 v121, v130, v129
	s_waitcnt lgkmcnt(4)
; #define LAS __attribute__((address_space(3)))
; DI float bf2f(bf16_t v) { return __uint_as_float(((unsigned)v) << 16); }
; DI bf16_t f2bf(float f) { return (bf16_t)(cvt_pk(f, 0.f) & 0xffffu); }
; DI float logsig16(float z) { return (fminf(z, 0.f) - __logf(1.0f + __expf(-fabsf(z)))) * (1.0f / 16.0f); }
; DI void gla_gate_phase(const Params& P, LAS unsigned char* lds, int lj) {
;     ...
;       for (int ii = 0; ii < 16; ++ii) {
;         const int i = ib * 16 + ii;
;         float z = bf_;
; #pragma unroll
;         for (int j4 = 0; j4 < 4; ++j4) { const f32x4 zz = *(const LAS f32x4*)(zL + i * 32 + j4 * 4); z += zz[0] * wf[j4 * 4] + zz[1] * wf[j4 * 4 + 1] + zz[2] * wf[j4 * 4 + 2] + zz[3] * wf[j4 * 4 + 3]; }
;         runf += logsig16(z);
;         const float Bi = totb - runb; runb += lsb[i];
;         const size_t tokrow = (size_t)item * 64 + i;
;         bf16_t* pr = proj + tokrow * 3072 + col;
;         const float q = bf2f(qraw[ii]), k = bf2f(kraw[ii]);
;         pr[0] = f2bf(q * __expf(runf)); pr[512] = f2bf(k * __expf(-runf));
;         QB[tokrow * 512 + col] = f2bf(q * __expf(Bi)); KB[tokrow * 512 + col] = f2bf(k * __expf(-Bi));
;       }
;       asm volatile("" ::: "memory");
;     }
;     dect[(size_t)item * 512 + col] = __expf(runf);
;     dect[(size_t)(512 + item) * 512 + col] = __expf(totb);
;   }
	v_add_f32_e32 v129, v129, v131
	v_mul_f32_e32 v120, 0x3fb8aa3b, v128
	v_exp_f32_e32 v120, v120
	s_nop 0
	v_mul_f32_e32 v120, v120, v74
	v_cvt_pk_bf16_f32 v120, v120, v1
	global_store_short v44, v120, s[46:47]
	v_mul_f32_e32 v120, 0xbfb8aa3b, v128
	v_exp_f32_e32 v120, v120
	s_nop 0
	v_mul_f32_e32 v120, v120, v82
	v_cvt_pk_bf16_f32 v120, v120, v1
	global_store_short v44, v120, s[46:47] offset:1024
	v_mul_f32_e32 v120, 0x3fb8aa3b, v121
	v_exp_f32_e32 v120, v120
	s_nop 0
	v_mul_f32_e32 v120, v120, v74
	v_cvt_pk_bf16_f32 v120, v120, v1
	global_store_short v46, v120, s[48:49] offset:2048
	v_mul_f32_e32 v120, 0xbfb8aa3b, v121
	v_exp_f32_e32 v120, v120
	s_nop 0
	v_mul_f32_e32 v120, v120, v82
	v_cvt_pk_bf16_f32 v120, v120, v1
	global_store_short v46, v120, s[50:51] offset:2048
	ds_read_b32 v131, v50 offset:14336
	v_add_u32_e32 v49, 0x400, v49
	ds_read_b128 v[84:87], v49 offset:0
	ds_read_b128 v[88:91], v49 offset:16
	ds_read_b128 v[92:95], v49 offset:32
	ds_read_b128 v[96:99], v49 offset:48
	s_waitcnt lgkmcnt(5)
	v_mul_f32_e32 v116, v3, v101
	v_fmac_f32_e32 v116, v2, v100
	v_fmac_f32_e32 v116, v4, v102
	v_fmac_f32_e32 v116, v5, v103
	v_add_f32_e32 v121, v34, v116
	v_mul_f32_e32 v116, v7, v105
	v_fmac_f32_e32 v116, v6, v104
	v_fmac_f32_e32 v116, v8, v106
	v_fmac_f32_e32 v116, v9, v107
	v_add_f32_e32 v121, v121, v116
	v_mul_f32_e32 v116, v11, v109
	v_fmac_f32_e32 v116, v10, v108
	v_fmac_f32_e32 v116, v12, v110
	v_fmac_f32_e32 v116, v13, v111
	v_add_f32_e32 v121, v121, v116
	v_mul_f32_e32 v116, v15, v113
	v_fmac_f32_e32 v116, v14, v112
	v_fmac_f32_e32 v116, v16, v114
	v_fmac_f32_e32 v116, v17, v115
	v_add_f32_e32 v121, v121, v116
	v_min_f32_e32 v117, 0, v121
	v_mul_f32_e64 v118, |v121|, s16
	v_exp_f32_e32 v118, v118
	s_nop 0
	v_add_f32_e32 v118, 1.0, v118
	v_log_f32_e32 v118, v118
	s_nop 0
	v_mul_f32_e32 v119, 0x3f317217, v118
	v_fma_f32 v119, v118, s55, -v119
	v_fmac_f32_e32 v119, 0x3377d1cf, v118
	v_fmac_f32_e32 v119, 0x3f317217, v118
	v_sub_f32_e32 v121, v117, v119
	v_fmac_f32_e32 v128, 0x3d800000, v121
	v_sub_f32_e32 v121, v130, v129
	s_waitcnt lgkmcnt(4)
	v_add_f32_e32 v129, v129, v131
	v_mul_f32_e32 v120, 0x3fb8aa3b, v128
	v_exp_f32_e32 v120, v120
	s_nop 0
	v_mul_f32_e32 v120, v120, v75
	v_cvt_pk_bf16_f32 v120, v120, v1
	global_store_short v45, v120, s[46:47]
	v_mul_f32_e32 v120, 0xbfb8aa3b, v128
	v_exp_f32_e32 v120, v120
	s_nop 0
	v_mul_f32_e32 v120, v120, v83
	v_cvt_pk_bf16_f32 v120, v120, v1
	global_store_short v45, v120, s[46:47] offset:1024
	v_mul_f32_e32 v120, 0x3fb8aa3b, v121
	v_exp_f32_e32 v120, v120
	s_nop 0
	v_mul_f32_e32 v120, v120, v75
	v_cvt_pk_bf16_f32 v120, v120, v1
	global_store_short v46, v120, s[48:49] offset:3072
	v_mul_f32_e32 v120, 0xbfb8aa3b, v121
	v_exp_f32_e32 v120, v120
	s_nop 0
	v_mul_f32_e32 v120, v120, v83
	v_cvt_pk_bf16_f32 v120, v120, v1
	global_store_short v46, v120, s[50:51] offset:3072
	v_add_u32_e32 v50, 0x4000, v50
	s_add_u32 s46, s46, 0xc000
	s_addc_u32 s47, s47, 0
	s_add_u32 s48, s48, 0x2000
	s_addc_u32 s49, s49, 0
	s_add_u32 s50, s50, 0x2000
	s_addc_u32 s51, s51, 0
	s_add_i32 s43, s43, 1
	s_cmp_lt_u32 s43, 8
	s_cbranch_scc1 .Lgt_main
	s_lshl_b32 s0, s42, 11
	s_add_u32 s0, s6, s0
	s_addc_u32 s1, s7, 0
	s_add_u32 s0, s0, 0xe00000
	s_addc_u32 s1, s1, 0
	v_mul_f32_e32 v120, 0x3fb8aa3b, v128
	v_exp_f32_e32 v120, v120
	v_mul_f32_e32 v121, 0x3fb8aa3b, v130
	v_exp_f32_e32 v121, v121
	global_store_dword v36, v120, s[0:1]
	s_add_u32 s0, s0, 0x100000
	s_addc_u32 s1, s1, 0
	global_store_dword v36, v121, s[0:1]
	s_add_i32 s42, s42, s10
	s_cmpk_lt_i32 s42, 0x200
	s_cbranch_scc1 .Lgt_item
